# GLA-out units redistributed by class load (FoX heavy 2, FoX light 3-4, scan WGs 2, SWA-only WGs 1) on top of SWA prologue wait removal
# baseline (speedup 1.0000x reference)
; __global__ void __launch_bounds__(512, 2) hybrid_fwd(Params p) {
;     ...
;             if (tid == 0) { unsigned* cw_ = (unsigned*)ws + 3584 + 64 * l; unsigned sp_ = 0;
;                 while (__hip_atomic_load(cw_, __ATOMIC_RELAXED, __HIP_MEMORY_SCOPE_AGENT) < 64u) { __builtin_amdgcn_s_sleep(2); if (++sp_ > (1u << 22)) break; }
;                 __builtin_amdgcn_fence(__ATOMIC_ACQUIRE, "agent"); asm volatile("s_waitcnt vmcnt(0)" ::: "memory"); }
;             __syncthreads();
;             for (int u = c; u < 512; u += G) gla_unit<1>(lds, tid, p, l, u >> 7, u & 127);
.LBB0_604:
	s_or_b64 exec, exec, s[0:1]
	v_readlane_b32 s3, v255, 58
	s_movk_i32 s32, 0x1ff
	s_nop 2
	s_cmp_eq_u32 s3, 0
	s_cbranch_scc1 .Lgla_go
	s_cmpk_lt_u32 s2, 76
	s_cbranch_scc1 .Lgla_A
	s_cmpk_lt_u32 s2, 112
	s_cbranch_scc1 .Lgla_B
	s_cmpk_lt_u32 s2, 128
	s_cbranch_scc1 .Lgla_C
	s_cmpk_lt_u32 s2, 192
	s_cbranch_scc1 .Lgla_D
	s_addk_i32 s2, 260
	s_movk_i32 s70, 64
	s_branch .Lgla_go
.Lgla_A:
	s_movk_i32 s70, 76
	s_movk_i32 s32, 151
	s_branch .Lgla_go
.Lgla_B:
	s_addk_i32 s2, 76
	s_movk_i32 s70, 36
	s_movk_i32 s32, 259
	s_branch .Lgla_go
.Lgla_C:
	s_addk_i32 s2, 148
	s_movk_i32 s70, 16
	s_movk_i32 s32, 323
	s_branch .Lgla_go
.Lgla_D:
	s_addk_i32 s2, 196
	s_movk_i32 s70, 64
	s_movk_i32 s32, 451
.Lgla_go:
	s_cmp_gt_i32 s2, s32
	s_waitcnt lgkmcnt(0)
	s_barrier
	s_cbranch_scc1 .LBB0_619
	v_readlane_b32 s0, v255, 42
	v_readlane_b32 s1, v255, 43
	s_lshl_b32 s72, s0, 7
	s_lshl_b64 s[0:1], s[72:73], 2
	v_readlane_b32 s4, v255, 4
	v_readlane_b32 s5, v255, 5
	s_add_u32 s80, s4, s0
	s_addc_u32 s81, s5, s1
	s_ashr_i32 s3, s2, 31
	s_ashr_i32 s71, s70, 31
	s_lshl_b64 s[92:93], s[2:3], 7
	s_lshl_b64 s[74:75], s[70:71], 7
	s_lshl_b32 s3, s2, 6
	s_lshl_b32 s39, s70, 6
	v_readlane_b32 s6, v255, 6
	v_readlane_b32 s7, v255, 7
	v_readlane_b32 s8, v255, 8
	v_readlane_b32 s9, v255, 9
	v_readlane_b32 s10, v255, 10
	v_readlane_b32 s11, v255, 11
	v_readlane_b32 s12, v255, 12
	v_readlane_b32 s13, v255, 13
	v_readlane_b32 s14, v255, 14
	v_readlane_b32 s15, v255, 15
	v_readlane_b32 s16, v255, 16
	v_readlane_b32 s17, v255, 17
	v_readlane_b32 s18, v255, 18
	v_readlane_b32 s19, v255, 19
	s_branch .LBB0_607
; __device__ __forceinline__ unsigned cvt_pk_bf16(float lo, float hi) { unsigned r; asm("v_cvt_pk_bf16_f32 %0, %1, %2" : "=v"(r) : "v"(lo), "v"(hi)); return r; }
; __device__ __forceinline__ float bflo(unsigned w) { return __uint_as_float(w << 16); }
; __device__ __forceinline__ float bfhi(unsigned w) { return __uint_as_float(w & 0xffff0000u); }
; template <int MODEC>
; __device__ __forceinline__ void gla_unit(LAS unsigned char* lds, const int tid_in, const Params& p, int l, int hh, int n) {
;     ...
;         __syncthreads();
;         const float tot = (ss[tt * 4] + ss[tt * 4 + 1]) + (ss[tt * 4 + 2] + ss[tt * 4 + 3]);
;         const float rstd = rsqrtf(tot * (1.f / 128.f) + EPS);
;         bf16_t* op = (bf16_t*)(ws + WS_O) + (size_t)(t0 + tt) * D_ + 1536 + hh * 128;
;         const bf16_t* grp = proj + (size_t)(t0 + tt) * NP + PJ_GR + hh * 128;
;         const float* gn = p.gla_norm + l * 128;
; #pragma unroll
;         for (int g = 0; g < 4; ++g) {
;             const int dv = 32 * dvb + 8 * g + 4 * h2;
;             const u32x2 gw = *(const u32x2*)(grp + dv); const f32x4 gnv = *(const f32x4*)(gn + dv);
;             const float g0 = bflo(gw.x), g1 = bfhi(gw.x), g2 = bflo(gw.y), g3 = bfhi(gw.y);
;             const float v0 = acc[4 * g] * rstd * gnv[0] * (g0 * __builtin_amdgcn_rcpf(1.f + __expf(-g0))), v1 = acc[4 * g + 1] * rstd * gnv[1] * (g1 * __builtin_amdgcn_rcpf(1.f + __expf(-g1)));
;             const float v2 = acc[4 * g + 2] * rstd * gnv[2] * (g2 * __builtin_amdgcn_rcpf(1.f + __expf(-g2))), v3 = acc[4 * g + 3] * rstd * gnv[3] * (g3 * __builtin_amdgcn_rcpf(1.f + __expf(-g3)));
;             u32x2 wv; wv.x = cvt_pk_bf16(v0, v1); wv.y = cvt_pk_bf16(v2, v3); *(u32x2*)(op + dv) = wv;
;         }
;         __syncthreads();
.LBB0_606:
	s_or_b64 exec, exec, s[0:1]
	v_add_u32_e32 v16, 0, v17
	s_waitcnt lgkmcnt(0)
	s_barrier
	ds_read_b128 v[16:19], v16 offset:37120
	s_ashr_i32 s77, s76, 31
	v_mov_b64_e32 v[22:23], s[34:35]
	s_lshl_b64 s[0:1], s[76:77], 1
	s_add_i32 s2, s2, s70
	s_waitcnt lgkmcnt(0)
	v_mov_b32_e32 v20, v17
	v_mov_b32_e32 v21, v18
	v_mov_b32_e32 v17, v19
	v_pk_add_f32 v[16:17], v[20:21], v[16:17]
	v_lshl_or_b32 v21, v89, 2, s45
	v_add_f32_e32 v16, v16, v17
	v_fmamk_f32 v16, v16, 0x3c000000, v240
	v_cmp_gt_f32_e32 vcc, s85, v16
	v_mul_f32_e32 v17, 0x4b800000, v16
	v_lshlrev_b32_e32 v200, 1, v21
	v_cndmask_b32_e32 v16, v16, v17, vcc
	v_rsq_f32_e32 v16, v16
	s_movk_i32 s45, 0x1000
	v_lshlrev_b32_e32 v21, 2, v21
	s_add_u32 s92, s92, s74
	v_mul_f32_e32 v17, 0x45800000, v16
	v_cndmask_b32_e32 v20, v16, v17, vcc
	v_add_u32_e32 v16, s44, v90
	v_ashrrev_i32_e32 v17, 31, v16
	v_lshlrev_b64 v[18:19], 12, v[16:17]
	v_mad_i64_i32 v[16:17], s[4:5], v16, s56, v[22:23]
	v_lshl_add_u64 v[18:19], s[86:87], 0, v[18:19]
	v_lshl_add_u64 v[16:17], v[16:17], 0, s[0:1]
	v_lshl_add_u64 v[18:19], v[18:19], 0, s[0:1]
	v_lshl_add_u64 v[22:23], v[16:17], 0, v[200:201]
	s_mov_b64 s[0:1], 0x1600
	v_lshl_add_u64 v[16:17], v[22:23], 0, s[0:1]
	v_add_co_u32_e32 v22, vcc, s45, v22
	v_mul_f32_e32 v29, v0, v20
	s_nop 0
	v_addc_co_u32_e32 v23, vcc, 0, v23, vcc
	flat_load_dwordx2 v[26:27], v[22:23] offset:1536
	v_mul_f32_e32 v31, v2, v20
	global_load_dwordx4 v[22:25], v21, s[80:81]
	v_mul_f32_e32 v33, v3, v20
	v_lshl_add_u64 v[18:19], v[18:19], 0, v[200:201]
	s_mov_b64 s[0:1], 0x24300c00
	s_addc_u32 s93, s93, s75
	s_add_i32 s3, s3, s39
	s_cmp_gt_i32 s2, s32
	s_waitcnt vmcnt(0) lgkmcnt(0)
	v_lshlrev_b32_e32 v28, 16, v26
	v_mul_f32_e32 v0, 0xbfb8aa3b, v28
	v_exp_f32_e32 v0, v0
	v_and_b32_e32 v26, 0xffff0000, v26
	v_mov_b32_e32 v35, v22
	v_lshlrev_b32_e32 v30, 16, v27
	v_add_f32_e32 v0, 1.0, v0
	v_rcp_f32_e32 v34, v0
	v_mul_f32_e32 v0, 0xbfb8aa3b, v26
	v_exp_f32_e32 v0, v0
	v_and_b32_e32 v32, 0xffff0000, v27
	v_mul_f32_e32 v27, v1, v20
	v_pk_mul_f32 v[28:29], v[34:35], v[28:29]
	v_add_f32_e32 v0, 1.0, v0
	v_rcp_f32_e32 v22, v0
	v_mul_f32_e32 v28, v28, v29
	v_pk_mul_f32 v[0:1], v[22:23], v[26:27]
	s_nop 0
	v_mul_f32_e32 v22, v0, v1
	v_mul_f32_e32 v0, 0xbfb8aa3b, v30
	v_exp_f32_e32 v0, v0
	v_mov_b32_e32 v1, v24
	v_cvt_pk_bf16_f32 v2, v28, v22
	v_mul_f32_e32 v26, v5, v20
	v_add_f32_e32 v0, 1.0, v0
	v_rcp_f32_e32 v0, v0
	v_mul_f32_e32 v28, v6, v20
	v_pk_mul_f32 v[0:1], v[0:1], v[30:31]
	s_nop 0
	v_mul_f32_e32 v23, v0, v1
	v_mul_f32_e32 v0, 0xbfb8aa3b, v32
	v_exp_f32_e32 v0, v0
	s_nop 0
	v_add_f32_e32 v0, 1.0, v0
	v_rcp_f32_e32 v24, v0
	s_nop 0
	v_pk_mul_f32 v[0:1], v[24:25], v[32:33]
	s_nop 0
	v_mul_f32_e32 v0, v0, v1
	v_cvt_pk_bf16_f32 v3, v23, v0
	v_lshl_add_u64 v[0:1], v[18:19], 0, s[0:1]
	s_mov_b32 s0, 0x24300000
	v_add_co_u32_e32 v18, vcc, s0, v18
	s_nop 1
	v_addc_co_u32_e32 v19, vcc, 0, v19, vcc
	flat_store_dwordx2 v[18:19], v[2:3] offset:3072
	flat_load_dwordx2 v[2:3], v[16:17] offset:16
	s_nop 0
	global_load_dwordx4 v[22:25], v21, s[80:81] offset:32
	v_mul_f32_e32 v18, v4, v20
	s_waitcnt vmcnt(0) lgkmcnt(0)
	v_lshlrev_b32_e32 v19, 16, v2
	v_and_b32_e32 v27, 0xffff0000, v2
	v_mul_f32_e32 v2, 0xbfb8aa3b, v19
	v_exp_f32_e32 v2, v2
	v_lshlrev_b32_e32 v29, 16, v3
	v_mov_b32_e32 v30, v22
	v_mov_b32_e32 v4, v23
	v_add_f32_e32 v2, 1.0, v2
	v_rcp_f32_e32 v31, v2
	v_mul_f32_e32 v2, 0xbfb8aa3b, v27
	v_exp_f32_e32 v2, v2
	v_and_b32_e32 v3, 0xffff0000, v3
	v_pk_mul_f32 v[18:19], v[30:31], v[18:19]
	v_add_f32_e32 v2, 1.0, v2
	v_rcp_f32_e32 v5, v2
	v_mul_f32_e32 v2, 0xbfb8aa3b, v29
	v_exp_f32_e32 v2, v2
	v_mul_f32_e32 v18, v18, v19
	v_pk_mul_f32 v[4:5], v[4:5], v[26:27]
	v_mul_f32_e32 v26, v8, v20
	v_add_f32_e32 v2, 1.0, v2
	v_mul_f32_e32 v19, v4, v5
	v_rcp_f32_e32 v5, v2
	v_mov_b32_e32 v4, v24
	v_mul_f32_e32 v2, v7, v20
	v_mul_f32_e32 v8, v9, v20
	v_pk_mul_f32 v[4:5], v[4:5], v[28:29]
	s_nop 0
	v_mul_f32_e32 v6, v4, v5
	v_mul_f32_e32 v4, 0xbfb8aa3b, v3
	v_exp_f32_e32 v4, v4
	s_nop 0
	v_add_f32_e32 v4, 1.0, v4
	v_rcp_f32_e32 v5, v4
	v_mov_b32_e32 v4, v25
	v_pk_mul_f32 v[2:3], v[4:5], v[2:3]
	s_nop 0
	v_mul_f32_e32 v3, v2, v3
	v_cvt_pk_bf16_f32 v2, v18, v19
	v_cvt_pk_bf16_f32 v3, v6, v3
	flat_store_dwordx2 v[0:1], v[2:3] offset:16
	flat_load_dwordx2 v[6:7], v[16:17] offset:32
	s_nop 0
	global_load_dwordx4 v[2:5], v21, s[80:81] offset:64
	s_waitcnt vmcnt(0) lgkmcnt(0)
	v_and_b32_e32 v23, 0xffff0000, v6
	v_mov_b32_e32 v18, v2
	v_mul_f32_e32 v2, 0xbfb8aa3b, v23
	v_exp_f32_e32 v2, v2
	v_mov_b32_e32 v22, v3
	v_lshlrev_b32_e32 v25, 16, v7
	v_mov_b32_e32 v24, v4
	v_add_f32_e32 v2, 1.0, v2
	v_rcp_f32_e32 v9, v2
	v_and_b32_e32 v7, 0xffff0000, v7
	v_lshlrev_b32_e32 v19, 16, v6
	v_mul_f32_e32 v6, 0xbfb8aa3b, v19
	v_pk_mul_f32 v[2:3], v[8:9], v[22:23]
	v_exp_f32_e32 v6, v6
	v_mul_f32_e32 v8, v2, v3
	v_mul_f32_e32 v3, 0xbfb8aa3b, v25
	v_exp_f32_e32 v3, v3
	v_mul_f32_e32 v2, v10, v20
	v_add_f32_e32 v6, 1.0, v6
	v_rcp_f32_e32 v27, v6
	v_add_f32_e32 v3, 1.0, v3
	v_rcp_f32_e32 v3, v3
	v_mov_b32_e32 v6, v5
	v_pk_mul_f32 v[18:19], v[26:27], v[18:19]
	v_pk_mul_f32 v[2:3], v[2:3], v[24:25]
	s_nop 0
	v_mul_f32_e32 v4, v2, v3
	v_mul_f32_e32 v3, 0xbfb8aa3b, v7
	v_exp_f32_e32 v3, v3
	v_mul_f32_e32 v2, v11, v20
	v_mul_f32_e32 v18, v18, v19
	v_add_f32_e32 v3, 1.0, v3
	v_rcp_f32_e32 v3, v3
	s_nop 0
	v_pk_mul_f32 v[2:3], v[2:3], v[6:7]
	s_nop 0
	v_mul_f32_e32 v3, v2, v3
	v_cvt_pk_bf16_f32 v2, v18, v8
	v_cvt_pk_bf16_f32 v3, v4, v3
	flat_store_dwordx2 v[0:1], v[2:3] offset:32
	flat_load_dwordx2 v[2:3], v[16:17] offset:48
	s_nop 0
	global_load_dwordx4 v[4:7], v21, s[80:81] offset:96
	v_mul_f32_e32 v18, v12, v20
	s_waitcnt vmcnt(0) lgkmcnt(0)
	v_lshlrev_b32_e32 v9, 16, v2
	v_and_b32_e32 v11, 0xffff0000, v2
	v_mul_f32_e32 v2, 0xbfb8aa3b, v9
	v_exp_f32_e32 v2, v2
	v_mov_b32_e32 v8, v4
	v_lshlrev_b32_e32 v17, 16, v3
	v_mov_b32_e32 v10, v5
	v_add_f32_e32 v2, 1.0, v2
	v_rcp_f32_e32 v19, v2
	v_mul_f32_e32 v2, 0xbfb8aa3b, v11
	v_exp_f32_e32 v2, v2
	v_and_b32_e32 v3, 0xffff0000, v3
	v_pk_mul_f32 v[8:9], v[18:19], v[8:9]
	v_mov_b32_e32 v16, v6
	v_add_f32_e32 v2, 1.0, v2
	v_mul_f32_e32 v12, v8, v9
	v_rcp_f32_e32 v9, v2
	v_mul_f32_e32 v2, 0xbfb8aa3b, v17
	v_exp_f32_e32 v2, v2
	v_mul_f32_e32 v8, v13, v20
	v_pk_mul_f32 v[4:5], v[8:9], v[10:11]
	v_add_f32_e32 v2, 1.0, v2
	v_mul_f32_e32 v8, v4, v5
	v_rcp_f32_e32 v5, v2
	v_mul_f32_e32 v2, 0xbfb8aa3b, v3
	v_exp_f32_e32 v2, v2
	v_mul_f32_e32 v4, v14, v20
	v_pk_mul_f32 v[4:5], v[4:5], v[16:17]
	v_add_f32_e32 v2, 1.0, v2
	v_mul_f32_e32 v6, v4, v5
	v_rcp_f32_e32 v5, v2
	v_mul_f32_e32 v4, v15, v20
	v_mov_b32_e32 v2, v7
	v_pk_mul_f32 v[2:3], v[4:5], v[2:3]
	s_nop 0
	v_mul_f32_e32 v3, v2, v3
	v_cvt_pk_bf16_f32 v2, v12, v8
	v_cvt_pk_bf16_f32 v3, v6, v3
	flat_store_dwordx2 v[0:1], v[2:3] offset:48
	s_waitcnt lgkmcnt(0)
	s_barrier
	s_cbranch_scc1 .LBB0_619
